# speedup vs baseline: 1.0342x; 1.0012x over previous
.LBB0_547:
	v_add_u32_e32 v164, v200, v202
	ds_read_b128 v[226:229], v164 offset:34816
	ds_read_b128 v[230:233], v164 offset:38912
	ds_read_b128 v[234:237], v164 offset:43008
	ds_read_b128 v[238:241], v164 offset:47104
	v_add_u32_e32 v164, v200, v203
	v_cvt_pk_bf16_f32 v222, v66, v67
	v_cvt_pk_bf16_f32 v223, v68, v69
	v_cvt_pk_bf16_f32 v224, v70, v71
	v_cvt_pk_bf16_f32 v225, v72, v73
	s_waitcnt lgkmcnt(3)
	v_mfma_f32_32x32x16_bf16 v[50:65], v[222:225], v[226:229], v[50:65]
	ds_read_b128 v[226:229], v164 offset:34816
	v_max_f32_e32 v247, v99, v99
	v_add_f32_e32 v156, 0, v66
	v_add_f32_e32 v157, 0, v67
	v_add_f32_e32 v156, v68, v156
	v_mov_b32_e32 v192, v219
	s_waitcnt lgkmcnt(3)
	v_mfma_f32_32x32x16_bf16 v[34:49], v[222:225], v[230:233], v[34:49]
	ds_read_b128 v[230:233], v164 offset:38912
	v_max_f32_e32 v248, v98, v98
	v_add_f32_e32 v157, v69, v157
	v_add_f32_e32 v156, v70, v156
	v_add_f32_e32 v157, v71, v157
	s_waitcnt lgkmcnt(3)
	v_mfma_f32_32x32x16_bf16 v[18:33], v[222:225], v[234:237], v[18:33]
	ds_read_b128 v[234:237], v164 offset:43008
	v_max_f32_e32 v247, v248, v247
	v_add_f32_e32 v156, v72, v156
	v_add_f32_e32 v157, v73, v157
	v_add_f32_e32 v156, v74, v156
	s_waitcnt lgkmcnt(3)
	v_mfma_f32_32x32x16_bf16 v[2:17], v[222:225], v[238:241], v[2:17]
	ds_read_b128 v[238:241], v164 offset:47104
	v_max3_f32 v247, v247, v100, v101
	v_add_f32_e32 v157, v75, v157
	v_add_f32_e32 v156, v76, v156
	v_add_f32_e32 v157, v77, v157
	v_add_u32_e32 v164, v200, v204
	v_cvt_pk_bf16_f32 v222, v74, v75
	v_cvt_pk_bf16_f32 v223, v76, v77
	v_cvt_pk_bf16_f32 v224, v78, v79
	v_cvt_pk_bf16_f32 v225, v80, v81
	s_waitcnt lgkmcnt(3)
	v_mfma_f32_32x32x16_bf16 v[50:65], v[222:225], v[226:229], v[50:65]
	ds_read_b128 v[226:229], v164 offset:34816
	v_max3_f32 v247, v247, v102, v103
	v_add_f32_e32 v156, v78, v156
	v_add_f32_e32 v157, v79, v157
	v_add_f32_e32 v156, v80, v156
	s_waitcnt lgkmcnt(3)
	v_mfma_f32_32x32x16_bf16 v[34:49], v[222:225], v[230:233], v[34:49]
	ds_read_b128 v[230:233], v164 offset:38912
	v_max3_f32 v247, v247, v104, v105
	v_add_f32_e32 v157, v81, v157
	v_add_f32_e32 v156, v82, v156
	v_add_f32_e32 v157, v83, v157
	s_waitcnt lgkmcnt(3)
	v_mfma_f32_32x32x16_bf16 v[18:33], v[222:225], v[234:237], v[18:33]
	ds_read_b128 v[234:237], v164 offset:43008
	v_max3_f32 v247, v247, v106, v107
	v_add_f32_e32 v156, v84, v156
	v_add_f32_e32 v157, v85, v157
	v_add_f32_e32 v156, v86, v156
	s_waitcnt lgkmcnt(3)
	v_mfma_f32_32x32x16_bf16 v[2:17], v[222:225], v[238:241], v[2:17]
	ds_read_b128 v[238:241], v164 offset:47104
	v_max3_f32 v247, v247, v108, v109
	v_add_f32_e32 v157, v87, v157
	v_add_f32_e32 v156, v88, v156
	v_add_f32_e32 v157, v89, v157
	v_add_u32_e32 v164, v200, v205
	v_cvt_pk_bf16_f32 v222, v82, v83
	v_cvt_pk_bf16_f32 v223, v84, v85
	v_cvt_pk_bf16_f32 v224, v86, v87
	v_cvt_pk_bf16_f32 v225, v88, v89
	s_waitcnt lgkmcnt(3)
	v_mfma_f32_32x32x16_bf16 v[50:65], v[222:225], v[226:229], v[50:65]
	ds_read_b128 v[226:229], v164 offset:34816
	v_max3_f32 v247, v247, v110, v111
	v_add_f32_e32 v156, v90, v156
	v_add_f32_e32 v157, v91, v157
	v_add_f32_e32 v156, v92, v156
	s_waitcnt lgkmcnt(3)
	v_mfma_f32_32x32x16_bf16 v[34:49], v[222:225], v[230:233], v[34:49]
	ds_read_b128 v[230:233], v164 offset:38912
	v_max3_f32 v254, v247, v112, v113
	v_add_f32_e32 v157, v93, v157
	v_add_f32_e32 v156, v94, v156
	v_add_f32_e32 v157, v95, v157
	s_waitcnt lgkmcnt(3)
	v_mfma_f32_32x32x16_bf16 v[18:33], v[222:225], v[234:237], v[18:33]
	ds_read_b128 v[234:237], v164 offset:43008
	v_max3_f32 v250, v254, v114, v115
	v_add_f32_e32 v156, v96, v156
	v_add_f32_e32 v157, v97, v157
	v_add_f32_e32 v156, v156, v157
	v_mov_b32_e32 v157, v156
	s_nop 1
	v_permlane32_swap_b32_e32 v156, v157
	v_add_f32_e32 v162, v156, v157
	s_waitcnt lgkmcnt(3)
	v_mfma_f32_32x32x16_bf16 v[2:17], v[222:225], v[238:241], v[2:17]
	ds_read_b128 v[238:241], v164 offset:47104
	v_max3_f32 v250, v250, v116, v117
	v_max3_f32 v250, v250, v118, v119
	v_cvt_pk_bf16_f32 v222, v90, v91
	v_cvt_pk_bf16_f32 v223, v92, v93
	v_cvt_pk_bf16_f32 v224, v94, v95
	v_cvt_pk_bf16_f32 v225, v96, v97
	v_cndmask_b32_e64 v164, v220, 1.0, vcc
	v_fmac_f32_e32 v162, v218, v164
	s_waitcnt lgkmcnt(3)
	v_mfma_f32_32x32x16_bf16 v[50:65], v[222:225], v[226:229], v[50:65]
	v_max3_f32 v250, v250, v120, v121
	v_max3_f32 v250, v250, v122, v123
	v_mov_b32_e32 v218, v162
	s_waitcnt lgkmcnt(2)
	v_mfma_f32_32x32x16_bf16 v[34:49], v[222:225], v[230:233], v[34:49]
	v_max3_f32 v250, v250, v124, v125
	v_max3_f32 v250, v250, v126, v127
	s_waitcnt lgkmcnt(1)
	v_mfma_f32_32x32x16_bf16 v[18:33], v[222:225], v[234:237], v[18:33]
	v_max3_f32 v250, v250, v128, v129
	s_waitcnt lgkmcnt(0)
	v_mfma_f32_32x32x16_bf16 v[2:17], v[222:225], v[238:241], v[2:17]

.LBB0_561:
	v_add_u32_e32 v164, v200, v202
	ds_read_b128 v[224:227], v164 offset:51200
	ds_read_b128 v[228:231], v164 offset:55296
	ds_read_b128 v[232:235], v164 offset:59392
	ds_read_b128 v[236:239], v164 offset:63488
	v_add_u32_e32 v164, v200, v203
	v_cvt_pk_bf16_f32 v220, v98, v99
	v_cvt_pk_bf16_f32 v221, v100, v101
	v_cvt_pk_bf16_f32 v222, v102, v103
	v_cvt_pk_bf16_f32 v223, v104, v105
	s_waitcnt lgkmcnt(3)
	v_mfma_f32_32x32x16_bf16 v[50:65], v[220:223], v[224:227], v[50:65]
	ds_read_b128 v[224:227], v164 offset:51200
	v_max_f32_e32 v247, v67, v67
	v_add_f32_e32 v156, 0, v98
	v_add_f32_e32 v157, 0, v99
	v_add_f32_e32 v156, v100, v156
	v_mov_b32_e32 v192, v189
	s_waitcnt lgkmcnt(3)
	v_mfma_f32_32x32x16_bf16 v[34:49], v[220:223], v[228:231], v[34:49]
	ds_read_b128 v[228:231], v164 offset:55296
	v_max_f32_e32 v248, v66, v66
	v_add_f32_e32 v157, v101, v157
	v_add_f32_e32 v156, v102, v156
	v_add_f32_e32 v157, v103, v157
	s_waitcnt lgkmcnt(3)
	v_mfma_f32_32x32x16_bf16 v[18:33], v[220:223], v[232:235], v[18:33]
	ds_read_b128 v[232:235], v164 offset:59392
	v_max_f32_e32 v247, v248, v247
	v_add_f32_e32 v156, v104, v156
	v_add_f32_e32 v157, v105, v157
	v_add_f32_e32 v156, v106, v156
	s_waitcnt lgkmcnt(3)
	v_mfma_f32_32x32x16_bf16 v[2:17], v[220:223], v[236:239], v[2:17]
	ds_read_b128 v[236:239], v164 offset:63488
	v_max3_f32 v247, v247, v68, v69
	v_add_f32_e32 v157, v107, v157
	v_add_f32_e32 v156, v108, v156
	v_add_f32_e32 v157, v109, v157
	v_add_u32_e32 v164, v200, v204
	v_cvt_pk_bf16_f32 v220, v106, v107
	v_cvt_pk_bf16_f32 v221, v108, v109
	v_cvt_pk_bf16_f32 v222, v110, v111
	v_cvt_pk_bf16_f32 v223, v112, v113
	s_waitcnt lgkmcnt(3)
	v_mfma_f32_32x32x16_bf16 v[50:65], v[220:223], v[224:227], v[50:65]
	ds_read_b128 v[224:227], v164 offset:51200
	v_max3_f32 v247, v247, v70, v71
	v_add_f32_e32 v156, v110, v156
	v_add_f32_e32 v157, v111, v157
	v_add_f32_e32 v156, v112, v156
	s_waitcnt lgkmcnt(3)
	v_mfma_f32_32x32x16_bf16 v[34:49], v[220:223], v[228:231], v[34:49]
	ds_read_b128 v[228:231], v164 offset:55296
	v_max3_f32 v247, v247, v72, v73
	v_add_f32_e32 v157, v113, v157
	v_add_f32_e32 v156, v114, v156
	v_add_f32_e32 v157, v115, v157
	s_waitcnt lgkmcnt(3)
	v_mfma_f32_32x32x16_bf16 v[18:33], v[220:223], v[232:235], v[18:33]
	ds_read_b128 v[232:235], v164 offset:59392
	v_max3_f32 v247, v247, v74, v75
	v_add_f32_e32 v156, v116, v156
	v_add_f32_e32 v157, v117, v157
	v_add_f32_e32 v156, v118, v156
	s_waitcnt lgkmcnt(3)
	v_mfma_f32_32x32x16_bf16 v[2:17], v[220:223], v[236:239], v[2:17]
	ds_read_b128 v[236:239], v164 offset:63488
	v_max3_f32 v247, v247, v76, v77
	v_add_f32_e32 v157, v119, v157
	v_add_f32_e32 v156, v120, v156
	v_add_f32_e32 v157, v121, v157
	v_add_u32_e32 v164, v200, v205
	v_cvt_pk_bf16_f32 v220, v114, v115
	v_cvt_pk_bf16_f32 v221, v116, v117
	v_cvt_pk_bf16_f32 v222, v118, v119
	v_cvt_pk_bf16_f32 v223, v120, v121
	s_waitcnt lgkmcnt(3)
	v_mfma_f32_32x32x16_bf16 v[50:65], v[220:223], v[224:227], v[50:65]
	ds_read_b128 v[224:227], v164 offset:51200
	v_max3_f32 v247, v247, v78, v79
	v_add_f32_e32 v156, v122, v156
	v_add_f32_e32 v157, v123, v157
	v_add_f32_e32 v156, v124, v156
	s_waitcnt lgkmcnt(3)
	v_mfma_f32_32x32x16_bf16 v[34:49], v[220:223], v[228:231], v[34:49]
	ds_read_b128 v[228:231], v164 offset:55296
	v_max3_f32 v249, v247, v80, v81
	v_add_f32_e32 v157, v125, v157
	v_add_f32_e32 v156, v126, v156
	v_add_f32_e32 v157, v127, v157
	s_waitcnt lgkmcnt(3)
	v_mfma_f32_32x32x16_bf16 v[18:33], v[220:223], v[232:235], v[18:33]
	ds_read_b128 v[232:235], v164 offset:59392
	v_max3_f32 v249, v249, v82, v83
	v_add_f32_e32 v156, v128, v156
	v_add_f32_e32 v157, v129, v157
	v_add_f32_e32 v156, v156, v157
	v_mov_b32_e32 v157, v156
	s_nop 1
	v_permlane32_swap_b32_e32 v156, v157
	v_add_f32_e32 v162, v156, v157
	s_waitcnt lgkmcnt(3)
	v_mfma_f32_32x32x16_bf16 v[2:17], v[220:223], v[236:239], v[2:17]
	ds_read_b128 v[236:239], v164 offset:63488
	v_max3_f32 v249, v249, v84, v85
	v_max3_f32 v249, v249, v86, v87
	v_cvt_pk_bf16_f32 v220, v122, v123
	v_cvt_pk_bf16_f32 v221, v124, v125
	v_cvt_pk_bf16_f32 v222, v126, v127
	v_cvt_pk_bf16_f32 v223, v128, v129
	v_cndmask_b32_e64 v164, v190, 1.0, vcc
	v_fmac_f32_e32 v162, v218, v164
	s_waitcnt lgkmcnt(3)
	v_mfma_f32_32x32x16_bf16 v[50:65], v[220:223], v[224:227], v[50:65]
	v_max3_f32 v249, v249, v88, v89
	v_max3_f32 v249, v249, v90, v91
	v_mov_b32_e32 v218, v162
	s_waitcnt lgkmcnt(2)
	v_mfma_f32_32x32x16_bf16 v[34:49], v[220:223], v[228:231], v[34:49]
	v_max3_f32 v249, v249, v92, v93
	v_max3_f32 v249, v249, v94, v95
	s_waitcnt lgkmcnt(1)
	v_mfma_f32_32x32x16_bf16 v[18:33], v[220:223], v[232:235], v[18:33]
	v_max3_f32 v249, v249, v96, v97
	s_waitcnt lgkmcnt(0)
	v_mfma_f32_32x32x16_bf16 v[2:17], v[220:223], v[236:239], v[2:17]
	s_or_b64 exec, exec, s[60:61]
	s_andn2_b64 vcc, exec, s[58:59]
	s_cbranch_vccnz .LBB0_554

.LBB0_1323:
	v_add_u32_e32 v234, v197, v199
	ds_read_b128 v[222:225], v234 offset:34816
	ds_read_b128 v[226:229], v234 offset:38912
	ds_read_b128 v[230:233], v234 offset:43008
	ds_read_b128 v[234:237], v234 offset:47104
	v_add_u32_e32 v238, v197, v200
	v_cvt_pk_bf16_f32 v218, v66, v67
	v_cvt_pk_bf16_f32 v219, v68, v69
	v_cvt_pk_bf16_f32 v220, v70, v71
	v_cvt_pk_bf16_f32 v221, v72, v73
	v_cndmask_b32_e64 v217, v217, 1.0, vcc
	s_waitcnt lgkmcnt(3)
	v_mfma_f32_32x32x16_bf16 v[50:65], v[218:221], v[222:225], v[50:65]
	ds_read_b128 v[222:225], v238 offset:34816
	v_max_f32_e32 v247, v83, v83
	v_add_f32_e32 v156, 0, v66
	v_add_f32_e32 v157, 0, v67
	v_add_f32_e32 v156, v68, v156
	v_mov_b32_e32 v188, v216
	s_waitcnt lgkmcnt(3)
	v_mfma_f32_32x32x16_bf16 v[34:49], v[218:221], v[226:229], v[34:49]
	ds_read_b128 v[226:229], v238 offset:38912
	v_max_f32_e32 v248, v82, v82
	v_add_f32_e32 v157, v69, v157
	v_add_f32_e32 v156, v70, v156
	v_add_f32_e32 v157, v71, v157
	s_waitcnt lgkmcnt(3)
	v_mfma_f32_32x32x16_bf16 v[18:33], v[218:221], v[230:233], v[18:33]
	ds_read_b128 v[230:233], v238 offset:43008
	v_max_f32_e32 v247, v248, v247
	v_add_f32_e32 v156, v72, v156
	v_add_f32_e32 v157, v73, v157
	v_add_f32_e32 v156, v74, v156
	s_waitcnt lgkmcnt(3)
	v_mfma_f32_32x32x16_bf16 v[2:17], v[218:221], v[234:237], v[2:17]
	ds_read_b128 v[234:237], v238 offset:47104
	v_max3_f32 v247, v247, v84, v85
	v_add_f32_e32 v157, v75, v157
	v_add_f32_e32 v156, v76, v156
	v_add_f32_e32 v157, v77, v157
	v_add_u32_e32 v238, v197, v201
	v_cvt_pk_bf16_f32 v218, v74, v75
	v_cvt_pk_bf16_f32 v219, v76, v77
	v_cvt_pk_bf16_f32 v220, v78, v79
	v_cvt_pk_bf16_f32 v221, v80, v81
	s_waitcnt lgkmcnt(3)
	v_mfma_f32_32x32x16_bf16 v[50:65], v[218:221], v[222:225], v[50:65]
	ds_read_b128 v[222:225], v238 offset:34816
	v_max3_f32 v247, v247, v86, v87
	v_add_f32_e32 v156, v78, v156
	v_add_f32_e32 v157, v79, v157
	v_add_f32_e32 v156, v80, v156
	s_waitcnt lgkmcnt(3)
	v_mfma_f32_32x32x16_bf16 v[34:49], v[218:221], v[226:229], v[34:49]
	ds_read_b128 v[226:229], v238 offset:38912
	v_max3_f32 v247, v247, v88, v89
	v_add_f32_e32 v157, v81, v157
	v_add_f32_e32 v156, v98, v156
	v_add_f32_e32 v157, v99, v157
	s_waitcnt lgkmcnt(3)
	v_mfma_f32_32x32x16_bf16 v[18:33], v[218:221], v[230:233], v[18:33]
	ds_read_b128 v[230:233], v238 offset:43008
	v_max3_f32 v247, v247, v90, v91
	v_add_f32_e32 v156, v100, v156
	v_add_f32_e32 v157, v101, v157
	v_add_f32_e32 v156, v102, v156
	s_waitcnt lgkmcnt(3)
	v_mfma_f32_32x32x16_bf16 v[2:17], v[218:221], v[234:237], v[2:17]
	ds_read_b128 v[234:237], v238 offset:47104
	v_max3_f32 v247, v247, v92, v93
	v_add_f32_e32 v157, v103, v157
	v_add_f32_e32 v156, v104, v156
	v_add_f32_e32 v157, v105, v157
	v_add_u32_e32 v238, v197, v202
	v_cvt_pk_bf16_f32 v218, v98, v99
	v_cvt_pk_bf16_f32 v219, v100, v101
	v_cvt_pk_bf16_f32 v220, v102, v103
	v_cvt_pk_bf16_f32 v221, v104, v105
	s_waitcnt lgkmcnt(3)
	v_mfma_f32_32x32x16_bf16 v[50:65], v[218:221], v[222:225], v[50:65]
	ds_read_b128 v[222:225], v238 offset:34816
	v_max3_f32 v247, v247, v94, v95
	v_add_f32_e32 v156, v106, v156
	v_add_f32_e32 v157, v107, v157
	v_add_f32_e32 v156, v108, v156
	s_waitcnt lgkmcnt(3)
	v_mfma_f32_32x32x16_bf16 v[34:49], v[218:221], v[226:229], v[34:49]
	ds_read_b128 v[226:229], v238 offset:38912
	v_max3_f32 v250, v247, v96, v97
	v_add_f32_e32 v157, v109, v157
	v_add_f32_e32 v156, v110, v156
	v_add_f32_e32 v157, v111, v157
	s_waitcnt lgkmcnt(3)
	v_mfma_f32_32x32x16_bf16 v[18:33], v[218:221], v[230:233], v[18:33]
	ds_read_b128 v[230:233], v238 offset:43008
	v_max3_f32 v247, v250, v114, v115
	v_add_f32_e32 v156, v112, v156
	v_add_f32_e32 v157, v113, v157
	v_add_f32_e32 v156, v156, v157
	v_mov_b32_e32 v157, v156
	s_nop 1
	v_permlane32_swap_b32_e32 v156, v157
	v_add_f32_e32 v189, v156, v157
	v_fmac_f32_e32 v189, v215, v217
	v_mov_b32_e32 v215, v189
	s_waitcnt lgkmcnt(3)
	v_mfma_f32_32x32x16_bf16 v[2:17], v[218:221], v[234:237], v[2:17]
	ds_read_b128 v[234:237], v238 offset:47104
	v_max3_f32 v247, v247, v116, v117
	v_max3_f32 v247, v247, v118, v119
	v_cvt_pk_bf16_f32 v218, v106, v107
	v_cvt_pk_bf16_f32 v219, v108, v109
	v_cvt_pk_bf16_f32 v220, v110, v111
	v_cvt_pk_bf16_f32 v221, v112, v113
	s_waitcnt lgkmcnt(3)
	v_mfma_f32_32x32x16_bf16 v[50:65], v[218:221], v[222:225], v[50:65]
	v_max3_f32 v247, v247, v120, v121
	v_max3_f32 v247, v247, v122, v123
	s_waitcnt lgkmcnt(2)
	v_mfma_f32_32x32x16_bf16 v[34:49], v[218:221], v[226:229], v[34:49]
	v_max3_f32 v247, v247, v124, v125
	v_max3_f32 v247, v247, v126, v127
	s_waitcnt lgkmcnt(1)
	v_mfma_f32_32x32x16_bf16 v[18:33], v[218:221], v[230:233], v[18:33]
	v_max3_f32 v250, v247, v128, v129
	s_waitcnt lgkmcnt(0)
	v_mfma_f32_32x32x16_bf16 v[2:17], v[218:221], v[234:237], v[2:17]

.LBB0_1337:
	v_add_u32_e32 v188, v197, v199
	ds_read_b128 v[220:223], v188 offset:51200
	ds_read_b128 v[224:227], v188 offset:55296
	ds_read_b128 v[228:231], v188 offset:59392
	ds_read_b128 v[232:235], v188 offset:63488
	v_add_u32_e32 v188, v197, v200
	v_cvt_pk_bf16_f32 v216, v82, v83
	v_cvt_pk_bf16_f32 v217, v84, v85
	v_cvt_pk_bf16_f32 v218, v86, v87
	v_cvt_pk_bf16_f32 v219, v88, v89
	v_cndmask_b32_e64 v187, v187, 1.0, vcc
	s_waitcnt lgkmcnt(3)
	v_mfma_f32_32x32x16_bf16 v[50:65], v[216:219], v[220:223], v[50:65]
	ds_read_b128 v[220:223], v188 offset:51200
	v_max_f32_e32 v247, v67, v67
	v_add_f32_e32 v156, 0, v82
	v_add_f32_e32 v157, 0, v83
	v_add_f32_e32 v156, v84, v156
	s_waitcnt lgkmcnt(3)
	v_mfma_f32_32x32x16_bf16 v[34:49], v[216:219], v[224:227], v[34:49]
	ds_read_b128 v[224:227], v188 offset:55296
	v_max_f32_e32 v248, v66, v66
	v_add_f32_e32 v157, v85, v157
	v_add_f32_e32 v156, v86, v156
	v_add_f32_e32 v157, v87, v157
	s_waitcnt lgkmcnt(3)
	v_mfma_f32_32x32x16_bf16 v[18:33], v[216:219], v[228:231], v[18:33]
	ds_read_b128 v[228:231], v188 offset:59392
	v_max_f32_e32 v247, v248, v247
	v_add_f32_e32 v156, v88, v156
	v_add_f32_e32 v157, v89, v157
	v_add_f32_e32 v156, v90, v156
	s_waitcnt lgkmcnt(3)
	v_mfma_f32_32x32x16_bf16 v[2:17], v[216:219], v[232:235], v[2:17]
	ds_read_b128 v[232:235], v188 offset:63488
	v_max3_f32 v247, v247, v68, v69
	v_add_f32_e32 v157, v91, v157
	v_add_f32_e32 v156, v92, v156
	v_add_f32_e32 v157, v93, v157
	v_add_u32_e32 v188, v197, v201
	v_cvt_pk_bf16_f32 v216, v90, v91
	v_cvt_pk_bf16_f32 v217, v92, v93
	v_cvt_pk_bf16_f32 v218, v94, v95
	v_cvt_pk_bf16_f32 v219, v96, v97
	s_waitcnt lgkmcnt(3)
	v_mfma_f32_32x32x16_bf16 v[50:65], v[216:219], v[220:223], v[50:65]
	ds_read_b128 v[220:223], v188 offset:51200
	v_max3_f32 v247, v247, v70, v71
	v_add_f32_e32 v156, v94, v156
	v_add_f32_e32 v157, v95, v157
	v_add_f32_e32 v156, v96, v156
	s_waitcnt lgkmcnt(3)
	v_mfma_f32_32x32x16_bf16 v[34:49], v[216:219], v[224:227], v[34:49]
	ds_read_b128 v[224:227], v188 offset:55296
	v_max3_f32 v247, v247, v72, v73
	v_add_f32_e32 v157, v97, v157
	v_add_f32_e32 v156, v114, v156
	v_add_f32_e32 v157, v115, v157
	s_waitcnt lgkmcnt(3)
	v_mfma_f32_32x32x16_bf16 v[18:33], v[216:219], v[228:231], v[18:33]
	ds_read_b128 v[228:231], v188 offset:59392
	v_max3_f32 v247, v247, v74, v75
	v_add_f32_e32 v156, v116, v156
	v_add_f32_e32 v157, v117, v157
	v_add_f32_e32 v156, v118, v156
	s_waitcnt lgkmcnt(3)
	v_mfma_f32_32x32x16_bf16 v[2:17], v[216:219], v[232:235], v[2:17]
	ds_read_b128 v[232:235], v188 offset:63488
	v_max3_f32 v247, v247, v76, v77
	v_add_f32_e32 v157, v119, v157
	v_add_f32_e32 v156, v120, v156
	v_add_f32_e32 v157, v121, v157
	v_add_u32_e32 v188, v197, v202
	v_cvt_pk_bf16_f32 v216, v114, v115
	v_cvt_pk_bf16_f32 v217, v116, v117
	v_cvt_pk_bf16_f32 v218, v118, v119
	v_cvt_pk_bf16_f32 v219, v120, v121
	s_waitcnt lgkmcnt(3)
	v_mfma_f32_32x32x16_bf16 v[50:65], v[216:219], v[220:223], v[50:65]
	ds_read_b128 v[220:223], v188 offset:51200
	v_max3_f32 v247, v247, v78, v79
	v_add_f32_e32 v156, v122, v156
	v_add_f32_e32 v157, v123, v157
	v_add_f32_e32 v156, v124, v156
	s_waitcnt lgkmcnt(3)
	v_mfma_f32_32x32x16_bf16 v[34:49], v[216:219], v[224:227], v[34:49]
	ds_read_b128 v[224:227], v188 offset:55296
	v_max3_f32 v249, v247, v80, v81
	v_add_f32_e32 v157, v125, v157
	v_add_f32_e32 v156, v126, v156
	v_add_f32_e32 v157, v127, v157
	s_waitcnt lgkmcnt(3)
	v_mfma_f32_32x32x16_bf16 v[18:33], v[216:219], v[228:231], v[18:33]
	ds_read_b128 v[228:231], v188 offset:59392
	v_max3_f32 v247, v249, v98, v99
	v_add_f32_e32 v156, v128, v156
	v_add_f32_e32 v157, v129, v157
	v_add_f32_e32 v156, v156, v157
	v_mov_b32_e32 v157, v156
	s_nop 1
	v_permlane32_swap_b32_e32 v156, v157
	v_add_f32_e32 v184, v156, v157
	v_fmac_f32_e32 v184, v215, v187
	v_mov_b32_e32 v215, v184
	s_waitcnt lgkmcnt(3)
	v_mfma_f32_32x32x16_bf16 v[2:17], v[216:219], v[232:235], v[2:17]
	ds_read_b128 v[232:235], v188 offset:63488
	v_max3_f32 v247, v247, v100, v101
	v_max3_f32 v247, v247, v102, v103
	v_cvt_pk_bf16_f32 v216, v122, v123
	v_cvt_pk_bf16_f32 v217, v124, v125
	v_cvt_pk_bf16_f32 v218, v126, v127
	v_cvt_pk_bf16_f32 v219, v128, v129
	v_mov_b32_e32 v188, v186
	s_waitcnt lgkmcnt(3)
	v_mfma_f32_32x32x16_bf16 v[50:65], v[216:219], v[220:223], v[50:65]
	v_max3_f32 v247, v247, v104, v105
	v_max3_f32 v247, v247, v106, v107
	s_waitcnt lgkmcnt(2)
	v_mfma_f32_32x32x16_bf16 v[34:49], v[216:219], v[224:227], v[34:49]
	v_max3_f32 v247, v247, v108, v109
	v_max3_f32 v247, v247, v110, v111
	s_waitcnt lgkmcnt(1)
	v_mfma_f32_32x32x16_bf16 v[18:33], v[216:219], v[228:231], v[18:33]
	v_max3_f32 v249, v247, v112, v113
	s_waitcnt lgkmcnt(0)
	v_mfma_f32_32x32x16_bf16 v[2:17], v[216:219], v[232:235], v[2:17]
	s_or_b64 exec, exec, s[56:57]
	s_andn2_b64 vcc, exec, s[54:55]
	s_cbranch_vccnz .LBB0_1330
